# MLA attention: XOR swizzle of the V tile in LDS (rows r and r+16 no longer share banks on the PV fragment reads)
# baseline (speedup 1.0000x reference)
.Lmla_prio_done:
	v_and_b32_e32 v4, 31, v146
	v_lshrrev_b32_e32 v0, 1, v146
	s_movk_i32 s2, 0x1e0
	v_and_or_b32 v153, v0, s2, v4
	v_add_u32_e32 v5, 0x200, v146
	s_movk_i32 s2, 0x100
	v_cmp_gt_u32_e64 s[10:11], s2, v146
	v_mul_u32_u24_e32 v7, 0x1556, v146
	v_mul_u32_u24_e32 v9, 0x1556, v5
	s_mov_b32 s2, 0x7060302
	v_lshrrev_b32_e32 v8, 16, v7
	v_lshrrev_b32_e32 v10, 16, v9
	v_perm_b32 v7, v9, v7, s2
	s_movk_i32 s4, 0x68
	v_mad_i32_i24 v5, v10, -12, v5
	v_pk_mul_lo_u16 v7, v7, s4 op_sel_hi:[1,0]
	v_bfe_u32 v1, v146, 5, 1
	v_and_b32_e32 v6, 56, v147
	v_lshlrev_b32_e32 v142, 3, v5
	v_lshrrev_b32_e32 v180, 16, v7
	v_lshlrev_b32_e32 v5, 4, v5
	v_lshlrev_b32_e32 v0, 3, v1
	v_lshl_add_u32 v181, v180, 1, v5
	v_lshlrev_b32_e32 v158, 1, v6
	v_mul_u32_u24_e32 v5, 0x68, v4
	v_lshlrev_b32_e32 v6, 4, v1
	v_lshlrev_b32_e32 v253, 2, v1
	v_mbcnt_hi_u32_b32 v1, -1, v145
	v_lshl_add_u32 v184, v5, 1, v6
	v_and_b32_e32 v5, 64, v1
	v_mov_b32_e32 v97, 0
	v_mul_u32_u24_e32 v96, 0x4200, v154
	v_mad_i32_i24 v9, v8, -12, v146
	v_mul_u32_u24_e32 v185, 0x48, v4
	v_xor_b32_e32 v4, 32, v1
	v_add_u32_e32 v5, 64, v5
	v_lshl_add_u64 v[2:3], s[12:13], 0, v[96:97]
	v_lshlrev_b32_e32 v138, 3, v9
	v_ashrrev_i32_e32 v143, 31, v142
	v_cmp_lt_i32_e32 vcc, v4, v5
	v_mov_b32_e32 v159, v97
	s_movk_i32 s2, 0xc00
	v_ashrrev_i32_e32 v139, 31, v138
	v_cndmask_b32_e32 v1, v1, v4, vcc
	v_lshl_add_u64 v[162:163], v[2:3], 0, v[158:159]
	v_lshlrev_b64 v[2:3], 1, v[142:143]
	v_and_b32_e32 v11, 0xfff8, v7
	v_lshlrev_b32_e32 v9, 4, v9
	v_mul_u32_u24_e32 v182, 0x48, v154
	v_lshlrev_b32_e32 v186, 2, v1
	v_and_b32_e32 v1, 7, v146
	v_mad_u64_u32 v[166:167], s[4:5], v10, s2, v[2:3]
	v_lshlrev_b64 v[2:3], 1, v[138:139]
	v_mul_hi_u32_u24_e32 v137, 0xc00, v8
	v_mul_u32_u24_e32 v136, 0xc00, v8
	v_mul_u32_u24_e32 v140, 0xc00, v10
	v_mov_b32_e32 v141, v97
	v_lshl_add_u32 v161, v11, 1, v9
	v_lshl_add_u32 v183, v182, 1, v158
	s_mov_b32 s39, 0
	v_lshl_or_b32 v159, v185, 1, v0
	v_lshl_or_b32 v164, v1, 4, v96
	v_mov_b32_e32 v165, v97
	v_mad_u64_u32 v[168:169], s[4:5], v8, s2, v[2:3]
	v_mov_b32_e32 v187, 0x2100
	v_mov_b64_e32 v[170:171], s[94:95]
	v_lshlrev_b32_e32 v172, 1, v0
	v_mov_b32_e32 v173, v97
	v_mov_b32_e32 v188, 0x108000
	v_mov_b32_e32 v189, 0xc0
	s_mov_b64 s[40:41], 0x100
	s_mov_b64 s[42:43], 0x60000
	v_lshlrev_b32_e32 v190, 1, v11
	s_mov_b32 s6, s3
	v_mov_b32_e32 v252, 0x12000
	v_lshl_add_u32 v252, v146, 6, v252
	v_add_u32_e32 v177, v180, v142
	v_lshlrev_b32_e32 v177, 1, v177
	v_lshl_add_u32 v179, v138, 1, v190
	v_lshrrev_b32_e32 v191, 4, v146
	v_and_b32_e32 v191, 8, v191
	v_add_u32_e32 v183, v183, v191
	v_lshlrev_b32_e32 v99, 1, v191
	v_sub_u32_e32 v191, v183, v99
	v_add_u32_e32 v191, 8, v191
	v_and_b32_e32 v99, 16, v146
	v_lshrrev_b32_e32 v99, 1, v99
	v_xor_b32_e32 v159, v159, v99
	s_branch .LBB0_2694

.LBB0_2701:
	s_or_b64 exec, exec, s[4:5]
	s_lshl_b32 s9, s9, 4
	s_add_i32 s9, s9, s7
	v_mad_i64_i32 v[10:11], s[4:5], s9, v188, v[162:163]
	global_load_dwordx4 v[4:7], v[10:11], off
	s_waitcnt vmcnt(1)
	ds_write_b128 v161, v[0:3]
	s_and_saveexec_b64 s[4:5], s[10:11]
	ds_write_b128 v181, v[124:127]
	s_or_b64 exec, exec, s[4:5]
	v_add_co_u32_e32 v0, vcc, 0x30000, v12
	s_waitcnt vmcnt(0)
	ds_write_b64 v183, v[4:5] offset:39936
	ds_write_b64 v191, v[6:7] offset:39936
	v_addc_co_u32_e32 v1, vcc, 0, v13, vcc
	global_load_dwordx4 v[0:3], v[0:1], off
	s_and_saveexec_b64 s[4:5], s[10:11]
	s_cbranch_execz .LBB0_2705
	v_add_co_u32_e32 v4, vcc, 0x30000, v8
	s_nop 1
	v_addc_co_u32_e32 v5, vcc, 0, v9, vcc
	global_load_dwordx4 v[124:127], v[4:5], off
.LBB0_2705:
	s_or_b64 exec, exec, s[4:5]
	global_load_dwordx4 v[4:7], v[10:11], off offset:128
	s_waitcnt vmcnt(1)
	ds_write_b128 v161, v[0:3] offset:13312
	s_and_saveexec_b64 s[4:5], s[10:11]
	ds_write_b128 v181, v[124:127] offset:13312
	s_or_b64 exec, exec, s[4:5]
	v_add_co_u32_e32 v0, vcc, 0x60000, v12
	s_waitcnt vmcnt(0)
	ds_write_b64 v183, v[4:5] offset:49152
	ds_write_b64 v191, v[6:7] offset:49152
	v_addc_co_u32_e32 v1, vcc, 0, v13, vcc
	global_load_dwordx4 v[128:131], v[0:1], off
	s_and_saveexec_b64 s[4:5], s[10:11]
	s_cbranch_execz .LBB0_2709
	v_add_co_u32_e32 v0, vcc, 0x60000, v8
	s_nop 1
	v_addc_co_u32_e32 v1, vcc, 0, v9, vcc
	global_load_dwordx4 v[124:127], v[0:1], off
.LBB0_2709:
	s_or_b64 exec, exec, s[4:5]
	global_load_dwordx4 v[132:135], v[10:11], off offset:256
	s_waitcnt lgkmcnt(0)
	s_barrier
	ds_read_b128 v[0:3], v184
	ds_read_b128 v[4:7], v184 offset:32
	s_waitcnt lgkmcnt(1)
	v_mfma_f32_32x32x16_bf16 v[48:63], v[0:3], v[100:103], 0
	s_mov_b32 s12, 0
	s_mov_b32 s13, s12
	s_mul_hi_i32 s5, s9, 0x108000
	s_mul_i32 s4, s9, 0x108000
	s_mov_b32 s14, s12
	s_mov_b32 s15, s12
	s_mov_b32 s16, s12
	s_waitcnt lgkmcnt(0)
	v_mfma_f32_32x32x16_bf16 v[48:63], v[4:7], v[104:107], v[48:63]
	ds_read_b128 v[0:3], v184 offset:64
	ds_read_b128 v[4:7], v184 offset:96
	s_mov_b32 s17, s12
	s_mov_b32 s18, s12
	s_mov_b32 s19, s12
	s_mov_b32 s20, s12
	s_mov_b32 s21, s12
	s_mov_b32 s22, s12
	s_waitcnt lgkmcnt(1)
	v_mfma_f32_32x32x16_bf16 v[48:63], v[0:3], v[108:111], v[48:63]
	s_mov_b32 s23, s12
	s_mov_b32 s24, s12
	s_mov_b32 s25, s12
	s_mov_b32 s26, s12
	s_mov_b32 s27, s12
	v_mov_b32_e32 v98, v164
	s_add_u32 s100, s90, s4
	s_addc_u32 s101, s91, s5
	s_add_u32 s100, s100, 0x1bc00180
	s_addc_u32 s101, s101, 0
	s_add_i32 s9, s8, -3
	s_waitcnt lgkmcnt(0)
	v_mfma_f32_32x32x16_bf16 v[48:63], v[4:7], v[112:115], v[48:63]
	ds_read_b128 v[0:3], v184 offset:128
	ds_read_b128 v[4:7], v184 offset:160
	ds_read_b128 v[20:23], v184 offset:6784
	ds_read_b128 v[64:67], v184 offset:6816
	v_mov_b32_e32 v192, 0
	ds_read_b128 v[16:19], v184 offset:6752
	s_waitcnt lgkmcnt(4)
	v_mfma_f32_32x32x16_bf16 v[48:63], v[0:3], v[116:119], v[48:63]
	ds_read_b128 v[0:3], v184 offset:6656
	s_waitcnt lgkmcnt(4)
	v_mfma_f32_32x32x16_bf16 v[48:63], v[4:7], v[120:123], v[48:63]
	ds_read_b128 v[4:7], v184 offset:6688
	s_waitcnt lgkmcnt(1)
	v_mfma_f32_32x32x16_bf16 v[32:47], v[0:3], v[100:103], 0
	ds_read_b128 v[0:3], v184 offset:6720
	s_waitcnt lgkmcnt(1)
	v_mfma_f32_32x32x16_bf16 v[32:47], v[4:7], v[104:107], v[32:47]
	s_waitcnt lgkmcnt(0)
	v_mfma_f32_32x32x16_bf16 v[32:47], v[0:3], v[108:111], v[32:47]
	v_mov_b64_e32 v[0:1], s[12:13]
	v_mov_b64_e32 v[14:15], s[26:27]
	v_mov_b64_e32 v[2:3], s[14:15]
	v_mov_b64_e32 v[4:5], s[16:17]
	v_mov_b64_e32 v[6:7], s[18:19]
	v_mov_b64_e32 v[8:9], s[20:21]
	v_mov_b64_e32 v[10:11], s[22:23]
	v_mfma_f32_32x32x16_bf16 v[32:47], v[16:19], v[112:115], v[32:47]
	v_mov_b32_e32 v176, v166
	v_mov_b32_e32 v178, v168
	v_mov_b64_e32 v[12:13], s[24:25]
	s_mul_i32 s98, s7, 0xc0
	s_add_u32 s98, s98, s44
	s_addc_u32 s99, s45, 0
	s_add_u32 s98, s98, s90
	s_addc_u32 s99, s99, s91
	s_add_u32 s98, s98, 0x15990000
	s_addc_u32 s99, s99, 0
	v_mfma_f32_32x32x16_bf16 v[32:47], v[20:23], v[116:119], v[32:47]
	v_mov_b64_e32 v[30:31], v[14:15]
	s_mov_b32 s13, 1
	s_mov_b32 s4, 2
	s_mov_b32 s16, 4
	v_mov_b64_e32 v[28:29], v[12:13]
	v_mov_b64_e32 v[26:27], v[10:11]
	v_mov_b64_e32 v[24:25], v[8:9]
	v_mfma_f32_32x32x16_bf16 v[32:47], v[64:67], v[120:123], v[32:47]
	v_mov_b64_e32 v[22:23], v[6:7]
	v_mov_b64_e32 v[20:21], v[4:5]
	v_mov_b64_e32 v[18:19], v[2:3]
	v_mov_b64_e32 v[16:17], v[0:1]
	ds_write_b128 v252, v[160:163]
	ds_write_b128 v252, v[164:167] offset:16
	ds_write_b128 v252, v[168:171] offset:32
	ds_write_b128 v252, v[172:175] offset:48
	s_nop 7
	s_nop 7
	v_max_f32_e32 v96, v48, v49
	v_max3_f32 v96, v96, v50, v51
	v_max3_f32 v96, v96, v52, v53
	v_max3_f32 v96, v96, v54, v55
	v_max3_f32 v96, v96, v56, v57
	v_max3_f32 v96, v96, v58, v59
	v_max3_f32 v96, v96, v60, v61
	v_max3_f32 v96, v96, v62, v63
	v_max3_f32 v96, v96, v32, v33
	v_max3_f32 v96, v96, v34, v35
	v_max3_f32 v96, v96, v36, v37
	v_max3_f32 v96, v96, v38, v39
	v_max3_f32 v96, v96, v40, v41
	v_max3_f32 v96, v96, v42, v43
	v_max3_f32 v96, v96, v44, v45
	v_max3_f32 v96, v96, v46, v47
	s_nop 1
	ds_bpermute_b32 v193, v186, v96
	s_waitcnt lgkmcnt(0)
	v_max_f32_e32 v96, v96, v193
	v_sub_f32_e32 v160, 0, v96
	v_sub_f32_e32 v161, 0, v96
	v_sub_f32_e32 v162, 0, v96
	v_sub_f32_e32 v163, 0, v96
	v_sub_f32_e32 v164, 0, v96
	v_sub_f32_e32 v165, 0, v96
	v_sub_f32_e32 v166, 0, v96
	v_sub_f32_e32 v167, 0, v96
	v_sub_f32_e32 v168, 0, v96
	v_sub_f32_e32 v169, 0, v96
	v_sub_f32_e32 v170, 0, v96
	v_sub_f32_e32 v171, 0, v96
	v_sub_f32_e32 v172, 0, v96
	v_sub_f32_e32 v173, 0, v96
	v_sub_f32_e32 v174, 0, v96
	v_sub_f32_e32 v175, 0, v96
	v_sub_f32_e32 v48, v48, v96
	v_sub_f32_e32 v49, v49, v96
	v_sub_f32_e32 v50, v50, v96
	v_sub_f32_e32 v51, v51, v96
	v_sub_f32_e32 v52, v52, v96
	v_sub_f32_e32 v53, v53, v96
	v_sub_f32_e32 v54, v54, v96
	v_sub_f32_e32 v55, v55, v96
	v_sub_f32_e32 v56, v56, v96
	v_sub_f32_e32 v57, v57, v96
	v_sub_f32_e32 v58, v58, v96
	v_sub_f32_e32 v59, v59, v96
	v_sub_f32_e32 v60, v60, v96
	v_sub_f32_e32 v61, v61, v96
	v_sub_f32_e32 v62, v62, v96
	v_sub_f32_e32 v63, v63, v96
	v_sub_f32_e32 v32, v32, v96
	v_sub_f32_e32 v33, v33, v96
	v_sub_f32_e32 v34, v34, v96
	v_sub_f32_e32 v35, v35, v96
	v_sub_f32_e32 v36, v36, v96
	v_sub_f32_e32 v37, v37, v96
	v_sub_f32_e32 v38, v38, v96
	v_sub_f32_e32 v39, v39, v96
	v_sub_f32_e32 v40, v40, v96
	v_sub_f32_e32 v41, v41, v96
	v_sub_f32_e32 v42, v42, v96
	v_sub_f32_e32 v43, v43, v96
	v_sub_f32_e32 v44, v44, v96
	v_sub_f32_e32 v45, v45, v96
	v_sub_f32_e32 v46, v46, v96
	v_sub_f32_e32 v47, v47, v96
.LBB0_2710:
	s_add_i32 s18, s16, -2
	s_cmp_lt_u32 s18, s8
	s_mov_b32 s17, s4
	s_cselect_b64 s[14:15], -1, 0
	s_cmp_ge_u32 s18, s8
	s_mul_i32 s19, s4, 0x3400
	s_barrier
	s_cbranch_scc1 .LBB0_2717
	v_add_u32_e32 v64, s19, v179
	s_waitcnt vmcnt(1)
	ds_write_b128 v64, v[128:131]
	s_and_saveexec_b64 s[4:5], s[10:11]
	v_add_u32_e32 v64, s19, v177
	ds_write_b128 v64, v[124:127]
	s_or_b64 exec, exec, s[4:5]
	s_mul_i32 s4, s17, 0x2400
	v_add_u32_e32 v64, s4, v183
	v_add_u32_e32 v99, s4, v191
	s_add_i32 s4, s16, -1
	s_cmp_ge_u32 s4, s8
	s_waitcnt vmcnt(0)
	ds_write_b64 v64, v[132:133] offset:39936
	ds_write_b64 v99, v[134:135] offset:39936
	s_cbranch_scc1 .LBB0_2717
	global_load_dwordx4 v[128:131], v178, s[98:99]
	s_and_saveexec_b64 s[4:5], s[10:11]
	s_cbranch_execz .LBB0_2716
	global_load_dwordx4 v[124:127], v176, s[98:99]

.LBB0_2719:
	v_exp_f32_e32 v193, v48
	v_exp_f32_e32 v195, v49
	s_waitcnt lgkmcnt(5)
	v_mfma_f32_32x32x16_bf16 v[80:95], v[228:231], v[116:119], v[80:95]
	ds_read_b128 v[228:231], v227 offset:6784
	v_exp_f32_e32 v196, v50
	v_exp_f32_e32 v197, v51
	s_waitcnt lgkmcnt(5)
	v_mfma_f32_32x32x16_bf16 v[80:95], v[232:235], v[120:123], v[80:95]
	ds_read_b128 v[232:235], v227 offset:6816
	v_exp_f32_e32 v199, v52
	v_exp_f32_e32 v200, v53
	s_waitcnt lgkmcnt(5)
	v_mfma_f32_32x32x16_bf16 v[64:79], v[236:239], v[100:103], v[160:175]
	v_exp_f32_e32 v201, v54
	v_exp_f32_e32 v202, v55
	s_waitcnt lgkmcnt(4)
	v_mfma_f32_32x32x16_bf16 v[64:79], v[240:243], v[104:107], v[64:79]
	v_exp_f32_e32 v203, v56
	v_exp_f32_e32 v204, v57
	s_waitcnt lgkmcnt(3)
	v_mfma_f32_32x32x16_bf16 v[64:79], v[244:247], v[108:111], v[64:79]
	v_exp_f32_e32 v205, v58
	s_waitcnt lgkmcnt(2)
	v_mfma_f32_32x32x16_bf16 v[64:79], v[248:251], v[112:115], v[64:79]
	s_mul_i32 s20, s12, 0x2400
	v_exp_f32_e32 v206, v59
	v_exp_f32_e32 v211, v32
	v_mov_b32_e32 v32, v33
	s_waitcnt lgkmcnt(1)
	v_mfma_f32_32x32x16_bf16 v[64:79], v[228:231], v[116:119], v[64:79]
	v_lshlrev_b32_e32 v33, 1, v185
	v_lshlrev_b32_e32 v96, 1, v253
	v_exp_f32_e32 v207, v60
	s_waitcnt lgkmcnt(0)
	v_mfma_f32_32x32x16_bf16 v[64:79], v[232:235], v[120:123], v[64:79]
	v_add_u32_e32 v52, s20, v159
	v_exp_f32_e32 v208, v61
	v_add_u32_e32 v58, 0xa800, v52
	v_exp_f32_e32 v209, v62
	v_add_u32_e32 v56, 0x9800, v52
	ds_read_b64 v[52:53], v58 offset:1536
	ds_read_b64 v[54:55], v58 offset:1552
	v_exp_f32_e32 v210, v63
	ds_read_b64 v[48:49], v56 offset:1024
	ds_read_b64 v[50:51], v56 offset:1040
	v_exp_f32_e32 v212, v32
	v_exp_f32_e32 v215, v36
	v_exp_f32_e32 v213, v34
	v_mov_b32_e32 v57, v35
	v_cvt_pk_bf16_f32 v32, v193, v195
	v_cvt_pk_bf16_f32 v33, v196, v197
	v_cvt_pk_bf16_f32 v34, v199, v200
	v_cvt_pk_bf16_f32 v35, v201, v202
	v_exp_f32_e32 v216, v37
	s_waitcnt lgkmcnt(2)
	v_mfma_f32_32x32x16_bf16 v[0:15], v[52:55], v[32:35], v[0:15]
	v_exp_f32_e32 v217, v38
	v_mov_b32_e32 v52, v39
	ds_read_b64 v[36:37], v58 offset:1568
	ds_read_b64 v[38:39], v58 offset:1584
	v_exp_f32_e32 v214, v57
	v_exp_f32_e32 v218, v52
	v_exp_f32_e32 v219, v40
	s_waitcnt lgkmcnt(2)
	v_mfma_f32_32x32x16_bf16 v[16:31], v[48:51], v[32:35], v[16:31]
	ds_read_b64 v[48:49], v56 offset:1056
	ds_read_b64 v[50:51], v56 offset:1072
	v_cvt_pk_bf16_f32 v32, v203, v204
	v_cvt_pk_bf16_f32 v33, v205, v206
	v_cvt_pk_bf16_f32 v34, v207, v208
	v_cvt_pk_bf16_f32 v35, v209, v210
	v_exp_f32_e32 v220, v41
	s_waitcnt lgkmcnt(2)
	v_mfma_f32_32x32x16_bf16 v[0:15], v[36:39], v[32:35], v[0:15]
	ds_read_b64 v[36:37], v58 offset:1600
	ds_read_b64 v[38:39], v58 offset:1616
	v_exp_f32_e32 v221, v42
	v_exp_f32_e32 v222, v43
	v_exp_f32_e32 v223, v44
	s_waitcnt lgkmcnt(2)
	v_mfma_f32_32x32x16_bf16 v[16:31], v[48:51], v[32:35], v[16:31]
	ds_read_b64 v[48:49], v56 offset:1088
	ds_read_b64 v[50:51], v56 offset:1104
	v_cvt_pk_bf16_f32 v32, v211, v212
	v_cvt_pk_bf16_f32 v33, v213, v214
	v_cvt_pk_bf16_f32 v34, v215, v216
	v_cvt_pk_bf16_f32 v35, v217, v218
	v_exp_f32_e32 v224, v45
	ds_read_b64 v[40:41], v56 offset:1120
	ds_read_b64 v[42:43], v56 offset:1136
	s_waitcnt lgkmcnt(4)
	v_mfma_f32_32x32x16_bf16 v[0:15], v[36:39], v[32:35], v[0:15]
	ds_read_b64 v[36:37], v58 offset:1632
	ds_read_b64 v[38:39], v58 offset:1648
	v_exp_f32_e32 v225, v46
	s_add_i32 s4, s16, -4
	s_cmp_ge_u32 s4, s9
	s_waitcnt lgkmcnt(0)
	s_barrier
	v_mfma_f32_32x32x16_bf16 v[16:31], v[48:51], v[32:35], v[16:31]
	v_exp_f32_e32 v226, v47
	v_cvt_pk_bf16_f32 v32, v219, v220
	v_cvt_pk_bf16_f32 v33, v221, v222
	v_cvt_pk_bf16_f32 v34, v223, v224
	v_cvt_pk_bf16_f32 v35, v225, v226
	s_nop 1
	v_mfma_f32_32x32x16_bf16 v[16:31], v[40:43], v[32:35], v[16:31]
	v_mfma_f32_32x32x16_bf16 v[0:15], v[36:39], v[32:35], v[0:15]
	s_cbranch_scc1 .LBB0_2726
	s_mul_i32 s21, s12, 0x3400
	v_add_u32_e32 v32, s21, v179
	s_waitcnt vmcnt(1)
	ds_write_b128 v32, v[128:131]
	s_and_saveexec_b64 s[4:5], s[10:11]
	v_add_u32_e32 v32, s21, v177
	ds_write_b128 v32, v[124:127]
	s_or_b64 exec, exec, s[4:5]
	v_add_u32_e32 v32, s20, v183
	v_add_u32_e32 v99, s20, v191
	s_cmp_ge_u32 s16, s8
	s_waitcnt vmcnt(0)
	ds_write_b64 v32, v[132:133] offset:39936
	ds_write_b64 v99, v[134:135] offset:39936
	s_cbranch_scc1 .LBB0_2726
	global_load_dwordx4 v[128:131], v178, s[98:99]
	s_and_saveexec_b64 s[4:5], s[10:11]
	s_cbranch_execz .LBB0_2725
	global_load_dwordx4 v[124:127], v176, s[98:99]
